# scan: prefetch loads issued by the idle half right after the staging barrier and by the P half after P (off the critical path)
# speedup vs baseline: 1.2154x; 1.0016x over previous
; DEV void scan_item_mfma(const Params& p, int g, int item, char* smem) {
;     ...
;     {
;       const int jt = wave >> 1, st = wave & 1;
;       const bool active = dir ? (st >= jt) : (st <= jt);
;       f32x16 pa;
; #pragma unroll
;       for (int i = 0; i < 16; ++i) pa[i] = 0.f;
;       if (active) {
;         bf16x8 qa[8], kb[8];
; #pragma unroll
;         for (int ks = 0; ks < 8; ++ks) {
;           qa[ks] = *(const bf16x8*)(Qs + (32 * jt + r) * 272 + ks * 32 + hh * 16);
;           kb[ks] = *(const bf16x8*)(Ks + (32 * st + r) * 272 + ks * 32 + hh * 16);
;         }
;         __builtin_amdgcn_sched_barrier(0);
;         f32x16 p1;
; #pragma unroll
;         for (int i = 0; i < 16; ++i) p1[i] = 0.f;
; #pragma unroll
;         for (int ks = 0; ks < 4; ++ks) {
;           pa = __builtin_amdgcn_mfma_f32_32x32x16_bf16(qa[2 * ks], kb[2 * ks], pa, 0, 0, 0);
;           p1 = __builtin_amdgcn_mfma_f32_32x32x16_bf16(qa[2 * ks + 1], kb[2 * ks + 1], p1, 0, 0, 0);
;         }
; #pragma unroll
;         for (int i = 0; i < 16; ++i) pa[i] += p1[i];
;       }
.Lsc0_p1ofa:
	s_waitcnt lgkmcnt(0)
	s_barrier
	s_cmp_eq_u32 s25, 4
	s_cbranch_scc0 .Lsc0_p2cfa
	s_cmp_gt_i32 s10, 0
	s_cselect_b32 s1, 1, 0
	s_sub_i32 s10, s10, s1
	s_mul_i32 s0, s1, 0x10000
	s_add_u32 s12, s12, s0
	s_addc_u32 s13, s13, 0
	s_mul_i32 s0, s1, 0x10000
	s_add_u32 s14, s14, s0
	s_addc_u32 s15, s15, 0
	s_mul_i32 s0, s1, 0x20000
	s_add_u32 s16, s16, s0
	s_addc_u32 s17, s17, 0
	s_mul_i32 s0, s1, 0x50000
	s_add_u32 s18, s18, s0
	s_addc_u32 s19, s19, 0
	s_mul_i32 s0, s1, 0x800
	s_add_u32 s20, s20, s0
	s_addc_u32 s21, s21, 0
	global_load_dwordx4 v[0:3], v209, s[12:13]
	global_load_dwordx4 v[4:7], v210, s[12:13]
	global_load_dwordx4 v[8:11], v209, s[14:15]
	global_load_dwordx4 v[12:15], v210, s[14:15]
	global_load_dwordx4 v[16:19], v213, s[16:17]
	global_load_dwordx4 v[20:23], v214, s[16:17]
	global_load_dwordx4 v[24:27], v215, s[18:19]
	global_load_dword v28, v216, s[20:21]
	s_branch .Lsc0_p2efa
.Lsc0_p2cfa:
	ds_read_b128 v[166:169], v240
	ds_read_b128 v[170:173], v240 offset:32
	ds_read_b128 v[174:177], v240 offset:64
	ds_read_b128 v[178:181], v240 offset:96
	ds_read_b128 v[182:185], v242 offset:17408
	ds_read_b128 v[186:189], v242 offset:17440
	ds_read_b128 v[190:193], v242 offset:17472
	ds_read_b128 v[194:197], v242 offset:17504
	s_waitcnt lgkmcnt(0)
	v_mfma_f32_32x32x16_bf16 v[144:159], v[182:185], v[166:169], 0
	v_mfma_f32_32x32x16_bf16 v[144:159], v[186:189], v[170:173], v[144:159]
	v_mfma_f32_32x32x16_bf16 v[144:159], v[190:193], v[174:177], v[144:159]
	v_mfma_f32_32x32x16_bf16 v[144:159], v[194:197], v[178:181], v[144:159]
	ds_read_b128 v[166:169], v240 offset:128
	ds_read_b128 v[170:173], v240 offset:160
	ds_read_b128 v[174:177], v240 offset:192
	ds_read_b128 v[178:181], v240 offset:224
	ds_read_b128 v[182:185], v242 offset:17536
	ds_read_b128 v[186:189], v242 offset:17568
	ds_read_b128 v[190:193], v242 offset:17600
	ds_read_b128 v[194:197], v242 offset:17632
	s_waitcnt lgkmcnt(0)
	v_mfma_f32_32x32x16_bf16 v[144:159], v[182:185], v[166:169], v[144:159]
	v_mfma_f32_32x32x16_bf16 v[144:159], v[186:189], v[170:173], v[144:159]
	v_mfma_f32_32x32x16_bf16 v[144:159], v[190:193], v[174:177], v[144:159]
	v_mfma_f32_32x32x16_bf16 v[144:159], v[194:197], v[178:181], v[144:159]
	s_nop 7
	s_nop 7
	s_cmp_eq_u32 s25, 0
	s_cbranch_scc1 .Lsc0_p2mfa
	s_cmp_eq_u32 s25, 3
	s_cbranch_scc0 .Lsc0_p2nfa

; DEV u16 f2bf(float f) { return (u16)(pack2(f, f) & 0xffffu); }
; DEV void scan_item_mfma(const Params& p, int g, int item, char* smem) {
;     ...
; #pragma unroll
;       for (int i = 0; i < 16; ++i) {
;         const int j = 32 * jt + (i & 3) + 8 * (i >> 2) + 4 * hh;
;         const int s_ = 32 * st + r;
;         const bool keep = dir ? (s_ >= j) : (s_ <= j);
;         *(u16*)(Ps + j * 144 + s_ * 2) = keep ? f2bf(pa[i]) : (u16)0;
;       }
.Lsc0_p2nfa:
	v_cvt_pk_bf16_f32 v144, v144, v145
	v_cvt_pk_bf16_f32 v145, v146, v147
	ds_write_b64 v239, v[144:145] offset:53248
	v_cvt_pk_bf16_f32 v148, v148, v149
	v_cvt_pk_bf16_f32 v149, v150, v151
	ds_write_b64 v239, v[148:149] offset:53264
	v_cvt_pk_bf16_f32 v152, v152, v153
	v_cvt_pk_bf16_f32 v153, v154, v155
	ds_write_b64 v239, v[152:153] offset:53280
	v_cvt_pk_bf16_f32 v156, v156, v157
	v_cvt_pk_bf16_f32 v157, v158, v159
	ds_write_b64 v239, v[156:157] offset:53296
	s_cmp_gt_i32 s10, 0
	s_cselect_b32 s1, 1, 0
	s_sub_i32 s10, s10, s1
	s_mul_i32 s0, s1, 0x10000
	s_add_u32 s12, s12, s0
	s_addc_u32 s13, s13, 0
	s_mul_i32 s0, s1, 0x10000
	s_add_u32 s14, s14, s0
	s_addc_u32 s15, s15, 0
	s_mul_i32 s0, s1, 0x20000
	s_add_u32 s16, s16, s0
	s_addc_u32 s17, s17, 0
	s_mul_i32 s0, s1, 0x50000
	s_add_u32 s18, s18, s0
	s_addc_u32 s19, s19, 0
	s_mul_i32 s0, s1, 0x800
	s_add_u32 s20, s20, s0
	s_addc_u32 s21, s21, 0
	global_load_dwordx4 v[0:3], v209, s[12:13]
	global_load_dwordx4 v[4:7], v210, s[12:13]
	global_load_dwordx4 v[8:11], v209, s[14:15]
	global_load_dwordx4 v[12:15], v210, s[14:15]
	global_load_dwordx4 v[16:19], v213, s[16:17]
	global_load_dwordx4 v[20:23], v214, s[16:17]
	global_load_dwordx4 v[24:27], v215, s[18:19]
	global_load_dword v28, v216, s[20:21]

.Lsc0_p1ofb:
	s_waitcnt lgkmcnt(0)
	s_barrier
	s_cmp_eq_u32 s25, 4
	s_cbranch_scc0 .Lsc0_p2cfb
	s_cmp_gt_i32 s10, 0
	s_cselect_b32 s1, 1, 0
	s_sub_i32 s10, s10, s1
	s_mul_i32 s0, s1, 0x10000
	s_add_u32 s12, s12, s0
	s_addc_u32 s13, s13, 0
	s_mul_i32 s0, s1, 0x10000
	s_add_u32 s14, s14, s0
	s_addc_u32 s15, s15, 0
	s_mul_i32 s0, s1, 0x20000
	s_add_u32 s16, s16, s0
	s_addc_u32 s17, s17, 0
	s_mul_i32 s0, s1, 0x50000
	s_add_u32 s18, s18, s0
	s_addc_u32 s19, s19, 0
	s_mul_i32 s0, s1, 0x800
	s_add_u32 s20, s20, s0
	s_addc_u32 s21, s21, 0
	global_load_dwordx4 v[32:35], v209, s[12:13]
	global_load_dwordx4 v[36:39], v210, s[12:13]
	global_load_dwordx4 v[40:43], v209, s[14:15]
	global_load_dwordx4 v[44:47], v210, s[14:15]
	global_load_dwordx4 v[48:51], v213, s[16:17]
	global_load_dwordx4 v[52:55], v214, s[16:17]
	global_load_dwordx4 v[56:59], v215, s[18:19]
	global_load_dword v60, v216, s[20:21]
	s_branch .Lsc0_p2efb

; DEV u16 f2bf(float f) { return (u16)(pack2(f, f) & 0xffffu); }
; DEV void scan_item_mfma(const Params& p, int g, int item, char* smem) {
;     ...
; #pragma unroll
;       for (int i = 0; i < 16; ++i) {
;         const int j = 32 * jt + (i & 3) + 8 * (i >> 2) + 4 * hh;
;         const int s_ = 32 * st + r;
;         const bool keep = dir ? (s_ >= j) : (s_ <= j);
;         *(u16*)(Ps + j * 144 + s_ * 2) = keep ? f2bf(pa[i]) : (u16)0;
;       }
.Lsc0_p2nfb:
	v_cvt_pk_bf16_f32 v144, v144, v145
	v_cvt_pk_bf16_f32 v145, v146, v147
	ds_write_b64 v239, v[144:145] offset:53248
	v_cvt_pk_bf16_f32 v148, v148, v149
	v_cvt_pk_bf16_f32 v149, v150, v151
	ds_write_b64 v239, v[148:149] offset:53264
	v_cvt_pk_bf16_f32 v152, v152, v153
	v_cvt_pk_bf16_f32 v153, v154, v155
	ds_write_b64 v239, v[152:153] offset:53280
	v_cvt_pk_bf16_f32 v156, v156, v157
	v_cvt_pk_bf16_f32 v157, v158, v159
	ds_write_b64 v239, v[156:157] offset:53296
	s_cmp_gt_i32 s10, 0
	s_cselect_b32 s1, 1, 0
	s_sub_i32 s10, s10, s1
	s_mul_i32 s0, s1, 0x10000
	s_add_u32 s12, s12, s0
	s_addc_u32 s13, s13, 0
	s_mul_i32 s0, s1, 0x10000
	s_add_u32 s14, s14, s0
	s_addc_u32 s15, s15, 0
	s_mul_i32 s0, s1, 0x20000
	s_add_u32 s16, s16, s0
	s_addc_u32 s17, s17, 0
	s_mul_i32 s0, s1, 0x50000
	s_add_u32 s18, s18, s0
	s_addc_u32 s19, s19, 0
	s_mul_i32 s0, s1, 0x800
	s_add_u32 s20, s20, s0
	s_addc_u32 s21, s21, 0
	global_load_dwordx4 v[32:35], v209, s[12:13]
	global_load_dwordx4 v[36:39], v210, s[12:13]
	global_load_dwordx4 v[40:43], v209, s[14:15]
	global_load_dwordx4 v[44:47], v210, s[14:15]
	global_load_dwordx4 v[48:51], v213, s[16:17]
	global_load_dwordx4 v[52:55], v214, s[16:17]
	global_load_dwordx4 v[56:59], v215, s[18:19]
	global_load_dword v60, v216, s[20:21]

.Lsc1_p1ofa:
	s_waitcnt lgkmcnt(0)
	s_barrier
	s_cmp_eq_u32 s25, 4
	s_cbranch_scc0 .Lsc1_p2cfa
	s_cmp_gt_i32 s10, 0
	s_cselect_b32 s1, 1, 0
	s_sub_i32 s10, s10, s1
	s_mul_i32 s0, s1, 0x10000
	s_sub_u32 s12, s12, s0
	s_subb_u32 s13, s13, 0
	s_mul_i32 s0, s1, 0x10000
	s_sub_u32 s14, s14, s0
	s_subb_u32 s15, s15, 0
	s_mul_i32 s0, s1, 0x20000
	s_sub_u32 s16, s16, s0
	s_subb_u32 s17, s17, 0
	s_mul_i32 s0, s1, 0x50000
	s_sub_u32 s18, s18, s0
	s_subb_u32 s19, s19, 0
	s_mul_i32 s0, s1, 0x800
	s_sub_u32 s20, s20, s0
	s_subb_u32 s21, s21, 0
	global_load_dwordx4 v[0:3], v209, s[12:13]
	global_load_dwordx4 v[4:7], v210, s[12:13]
	global_load_dwordx4 v[8:11], v209, s[14:15]
	global_load_dwordx4 v[12:15], v210, s[14:15]
	global_load_dwordx4 v[16:19], v213, s[16:17]
	global_load_dwordx4 v[20:23], v214, s[16:17]
	global_load_dwordx4 v[24:27], v215, s[18:19]
	global_load_dword v28, v216, s[20:21]
	s_branch .Lsc1_p2efa

; DEV u16 f2bf(float f) { return (u16)(pack2(f, f) & 0xffffu); }
; DEV void scan_item_mfma(const Params& p, int g, int item, char* smem) {
;     ...
; #pragma unroll
;       for (int i = 0; i < 16; ++i) {
;         const int j = 32 * jt + (i & 3) + 8 * (i >> 2) + 4 * hh;
;         const int s_ = 32 * st + r;
;         const bool keep = dir ? (s_ >= j) : (s_ <= j);
;         *(u16*)(Ps + j * 144 + s_ * 2) = keep ? f2bf(pa[i]) : (u16)0;
;       }
.Lsc1_p2nfa:
	v_cvt_pk_bf16_f32 v144, v144, v145
	v_cvt_pk_bf16_f32 v145, v146, v147
	ds_write_b64 v239, v[144:145] offset:53248
	v_cvt_pk_bf16_f32 v148, v148, v149
	v_cvt_pk_bf16_f32 v149, v150, v151
	ds_write_b64 v239, v[148:149] offset:53264
	v_cvt_pk_bf16_f32 v152, v152, v153
	v_cvt_pk_bf16_f32 v153, v154, v155
	ds_write_b64 v239, v[152:153] offset:53280
	v_cvt_pk_bf16_f32 v156, v156, v157
	v_cvt_pk_bf16_f32 v157, v158, v159
	ds_write_b64 v239, v[156:157] offset:53296
	s_cmp_gt_i32 s10, 0
	s_cselect_b32 s1, 1, 0
	s_sub_i32 s10, s10, s1
	s_mul_i32 s0, s1, 0x10000
	s_sub_u32 s12, s12, s0
	s_subb_u32 s13, s13, 0
	s_mul_i32 s0, s1, 0x10000
	s_sub_u32 s14, s14, s0
	s_subb_u32 s15, s15, 0
	s_mul_i32 s0, s1, 0x20000
	s_sub_u32 s16, s16, s0
	s_subb_u32 s17, s17, 0
	s_mul_i32 s0, s1, 0x50000
	s_sub_u32 s18, s18, s0
	s_subb_u32 s19, s19, 0
	s_mul_i32 s0, s1, 0x800
	s_sub_u32 s20, s20, s0
	s_subb_u32 s21, s21, 0
	global_load_dwordx4 v[0:3], v209, s[12:13]
	global_load_dwordx4 v[4:7], v210, s[12:13]
	global_load_dwordx4 v[8:11], v209, s[14:15]
	global_load_dwordx4 v[12:15], v210, s[14:15]
	global_load_dwordx4 v[16:19], v213, s[16:17]
	global_load_dwordx4 v[20:23], v214, s[16:17]
	global_load_dwordx4 v[24:27], v215, s[18:19]
	global_load_dword v28, v216, s[20:21]

.Lsc1_p1ofb:
	s_waitcnt lgkmcnt(0)
	s_barrier
	s_cmp_eq_u32 s25, 4
	s_cbranch_scc0 .Lsc1_p2cfb
	s_cmp_gt_i32 s10, 0
	s_cselect_b32 s1, 1, 0
	s_sub_i32 s10, s10, s1
	s_mul_i32 s0, s1, 0x10000
	s_sub_u32 s12, s12, s0
	s_subb_u32 s13, s13, 0
	s_mul_i32 s0, s1, 0x10000
	s_sub_u32 s14, s14, s0
	s_subb_u32 s15, s15, 0
	s_mul_i32 s0, s1, 0x20000
	s_sub_u32 s16, s16, s0
	s_subb_u32 s17, s17, 0
	s_mul_i32 s0, s1, 0x50000
	s_sub_u32 s18, s18, s0
	s_subb_u32 s19, s19, 0
	s_mul_i32 s0, s1, 0x800
	s_sub_u32 s20, s20, s0
	s_subb_u32 s21, s21, 0
	global_load_dwordx4 v[32:35], v209, s[12:13]
	global_load_dwordx4 v[36:39], v210, s[12:13]
	global_load_dwordx4 v[40:43], v209, s[14:15]
	global_load_dwordx4 v[44:47], v210, s[14:15]
	global_load_dwordx4 v[48:51], v213, s[16:17]
	global_load_dwordx4 v[52:55], v214, s[16:17]
	global_load_dwordx4 v[56:59], v215, s[18:19]
	global_load_dword v60, v216, s[20:21]
	s_branch .Lsc1_p2efb

; DEV u16 f2bf(float f) { return (u16)(pack2(f, f) & 0xffffu); }
; DEV void scan_item_mfma(const Params& p, int g, int item, char* smem) {
;     ...
; #pragma unroll
;       for (int i = 0; i < 16; ++i) {
;         const int j = 32 * jt + (i & 3) + 8 * (i >> 2) + 4 * hh;
;         const int s_ = 32 * st + r;
;         const bool keep = dir ? (s_ >= j) : (s_ <= j);
;         *(u16*)(Ps + j * 144 + s_ * 2) = keep ? f2bf(pa[i]) : (u16)0;
;       }
.Lsc1_p2nfb:
	v_cvt_pk_bf16_f32 v144, v144, v145
	v_cvt_pk_bf16_f32 v145, v146, v147
	ds_write_b64 v239, v[144:145] offset:53248
	v_cvt_pk_bf16_f32 v148, v148, v149
	v_cvt_pk_bf16_f32 v149, v150, v151
	ds_write_b64 v239, v[148:149] offset:53264
	v_cvt_pk_bf16_f32 v152, v152, v153
	v_cvt_pk_bf16_f32 v153, v154, v155
	ds_write_b64 v239, v[152:153] offset:53280
	v_cvt_pk_bf16_f32 v156, v156, v157
	v_cvt_pk_bf16_f32 v157, v158, v159
	ds_write_b64 v239, v[156:157] offset:53296
	s_cmp_gt_i32 s10, 0
	s_cselect_b32 s1, 1, 0
	s_sub_i32 s10, s10, s1
	s_mul_i32 s0, s1, 0x10000
	s_sub_u32 s12, s12, s0
	s_subb_u32 s13, s13, 0
	s_mul_i32 s0, s1, 0x10000
	s_sub_u32 s14, s14, s0
	s_subb_u32 s15, s15, 0
	s_mul_i32 s0, s1, 0x20000
	s_sub_u32 s16, s16, s0
	s_subb_u32 s17, s17, 0
	s_mul_i32 s0, s1, 0x50000
	s_sub_u32 s18, s18, s0
	s_subb_u32 s19, s19, 0
	s_mul_i32 s0, s1, 0x800
	s_sub_u32 s20, s20, s0
	s_subb_u32 s21, s21, 0
	global_load_dwordx4 v[32:35], v209, s[12:13]
	global_load_dwordx4 v[36:39], v210, s[12:13]
	global_load_dwordx4 v[40:43], v209, s[14:15]
	global_load_dwordx4 v[44:47], v210, s[14:15]
	global_load_dwordx4 v[48:51], v213, s[16:17]
	global_load_dwordx4 v[52:55], v214, s[16:17]
	global_load_dwordx4 v[56:59], v215, s[18:19]
	global_load_dword v60, v216, s[20:21]
